# v13: P1 in-proj epilogue writes full 128B lines (B-fragment LDS remap so a wave owns 64 contiguous columns + DPP half-row exchange + saddr stores)
# speedup vs baseline: 1.0038x; 1.0038x over previous
.LBB0_364:
	s_add_u32 s12, s46, 0x7100000
	s_addc_u32 s13, s47, 0
	s_lshl_b32 s3, s3, 5
	s_mov_b64 s[14:15], 0x80
	s_and_b32 s3, s3, 0x60
	s_add_i32 m0, s9, 0x18000
	v_lshl_add_u64 v[8:9], v[8:9], 0, s[14:15]
	s_lshl_b32 s7, s2, 13
	s_lshl_b32 s17, s3, 7
	s_waitcnt vmcnt(2)
	s_barrier
	global_load_lds_dwordx4 v[8:9], off
	v_lshl_add_u64 v[6:7], v[6:7], 0, s[14:15]
	s_add_i32 m0, s9, 0x1a000
	s_add_i32 s40, s9, 0x8000
	s_add_i32 s41, s9, 0xa000
	global_load_lds_dwordx4 v[6:7], off
	v_lshl_add_u64 v[2:3], v[2:3], 0, s[14:15]
	s_mov_b32 m0, s40
	s_add_u32 s4, s28, 0x40080
	global_load_lds_dwordx4 v[2:3], off
	v_lshl_add_u64 v[2:3], v[4:5], 0, s[14:15]
	s_mov_b32 m0, s41
	s_addc_u32 s5, s29, 0
	global_load_lds_dwordx4 v[2:3], off
	s_add_i32 m0, s9, 0x1c000
	v_lshl_add_u64 v[2:3], s[4:5], 0, v[132:133]
	global_load_lds_dwordx4 v[2:3], off
	v_lshl_add_u64 v[2:3], s[4:5], 0, v[136:137]
	s_add_i32 m0, s9, 0x1e000
	v_lshlrev_b32_e32 v4, 2, v1
	global_load_lds_dwordx4 v[2:3], off
	v_and_b32_e32 v2, 15, v1
	v_lshlrev_b32_e32 v3, 1, v14
	v_lshl_or_b32 v141, s2, 6, v2
	v_lshl_or_b32 v2, v2, 6, v3
	v_and_b32_e32 v4, 32, v4
	v_bitop3_b32 v5, v2, s7, v4 bitop3:0xde
	v_lshlrev_b32_e32 v2, 6, v1
	s_movk_i32 s2, 0x3c0
	v_or_b32_e32 v140, s3, v14
	v_and_or_b32 v2, v2, s2, v3
	v_lshlrev_b32_e32 v138, 2, v140
	v_bitop3_b32 v156, s17, v2, v4 bitop3:0xf6
	v_lshl_add_u64 v[2:3], s[46:47], 0, v[138:139]
	s_mov_b64 s[4:5], 0x2000000
	v_lshl_add_u64 v[142:143], v[2:3], 0, s[4:5]
	v_lshlrev_b32_e32 v2, 8, v1
	v_and_b32_e32 v2, 0x38000, v2
	v_lshlrev_b32_e32 v3, 11, v12
	v_or3_b32 v2, v10, v2, v3
	v_add_u32_e32 v144, v2, v11
	v_lshlrev_b32_e32 v2, 4, v13
	s_waitcnt vmcnt(6)
	s_cmpk_lt_u32 s16, 0x100
	v_and_b32_e32 v2, 0x78000, v2
	s_cselect_b64 s[16:17], -1, 0
	v_or3_b32 v2, v10, v2, v3
	s_add_i32 s44, 0, 0x10000
	s_add_i32 s45, 0, 0x14000
	v_cmp_gt_u32_e64 s[2:3], 16, v140
	s_ashr_i32 s42, s91, 31
	s_ashr_i32 s43, s85, 31
	v_mov_b32_e32 v145, v139
	v_add_u32_e32 v146, v2, v11
	v_mov_b32_e32 v147, v139
	v_mov_b64_e32 v[148:149], 0x3fc
	v_mov_b64_e32 v[150:151], 0x3fb
	v_and_b32_e32 v158, 0x60, v140
	v_lshl_add_u32 v156, v158, 7, v156
	v_add_u32_e32 v157, s44, v156
	v_add_u32_e32 v158, 0x1000, v157
	v_add_u32_e32 v159, 0, v5
	s_movk_i32 s56, 0x1c00
	s_barrier
	s_branch .LBB0_367

.LBB0_374:
	ds_read_b128 v[152:155], v157
	ds_read_b128 v[160:163], v157 offset:1024
	ds_read_b128 v[164:167], v157 offset:2048
	ds_read_b128 v[168:171], v157 offset:3072
	ds_read_b128 v[172:175], v158
	ds_read_b128 v[176:179], v158 offset:1024
	ds_read_b128 v[180:183], v158 offset:2048
	ds_read_b128 v[184:187], v158 offset:3072
	s_add_u32 s28, s26, 0xfffc0080
	s_addc_u32 s29, s27, -1
	s_cmp_eq_u32 s80, 12
	s_cselect_b32 s31, s7, s29
	s_cselect_b32 s30, s21, s28
	s_cselect_b32 s29, s19, s59
	s_cselect_b32 s28, s57, s58
	v_lshl_add_u64 v[222:223], s[26:27], 0, v[144:145]
	s_add_i32 m0, s9, 0xc000
	ds_read_b128 v[188:191], v159
	ds_read_b128 v[192:195], v159 offset:1024
	ds_read_b128 v[196:199], v159 offset:2048
	ds_read_b128 v[200:203], v159 offset:3072
	ds_read_b128 v[204:207], v159 offset:4096
	ds_read_b128 v[210:213], v159 offset:5120
	ds_read_b128 v[214:217], v159 offset:6144
	ds_read_b128 v[218:221], v159 offset:7168
	global_load_lds_dwordx4 v[222:223], off
	v_lshl_add_u64 v[222:223], s[26:27], 0, v[146:147]
	s_add_i32 m0, s9, 0xe000
	s_nop 0
	global_load_lds_dwordx4 v[222:223], off
	s_waitcnt vmcnt(8)
	s_waitcnt lgkmcnt(0)
	s_barrier
	s_setprio 1
	s_waitcnt lgkmcnt(0)
	v_mfma_f32_16x16x32_bf16 v[126:129], v[152:155], v[188:191], v[126:129]
	v_mfma_f32_16x16x32_bf16 v[122:125], v[164:167], v[188:191], v[122:125]
	v_mfma_f32_16x16x32_bf16 v[110:113], v[152:155], v[196:199], v[110:113]
	v_mfma_f32_16x16x32_bf16 v[106:109], v[164:167], v[196:199], v[106:109]
	v_mfma_f32_16x16x32_bf16 v[94:97], v[152:155], v[204:207], v[94:97]
	v_mfma_f32_16x16x32_bf16 v[90:93], v[164:167], v[204:207], v[90:93]
	v_mfma_f32_16x16x32_bf16 v[78:81], v[152:155], v[214:217], v[78:81]
	v_mfma_f32_16x16x32_bf16 v[74:77], v[164:167], v[214:217], v[74:77]
	v_mfma_f32_16x16x32_bf16 v[126:129], v[160:163], v[192:195], v[126:129]
	v_mfma_f32_16x16x32_bf16 v[122:125], v[168:171], v[192:195], v[122:125]
	v_mfma_f32_16x16x32_bf16 v[110:113], v[160:163], v[200:203], v[110:113]
	v_mfma_f32_16x16x32_bf16 v[106:109], v[168:171], v[200:203], v[106:109]
	v_mfma_f32_16x16x32_bf16 v[94:97], v[160:163], v[210:213], v[94:97]
	v_mfma_f32_16x16x32_bf16 v[90:93], v[168:171], v[210:213], v[90:93]
	v_mfma_f32_16x16x32_bf16 v[78:81], v[160:163], v[218:221], v[78:81]
	v_mfma_f32_16x16x32_bf16 v[74:77], v[168:171], v[218:221], v[74:77]
	s_setprio 0
	s_setprio 1
	v_mfma_f32_16x16x32_bf16 v[118:121], v[172:175], v[188:191], v[118:121]
	v_mfma_f32_16x16x32_bf16 v[114:117], v[180:183], v[188:191], v[114:117]
	v_mfma_f32_16x16x32_bf16 v[102:105], v[172:175], v[196:199], v[102:105]
	v_mfma_f32_16x16x32_bf16 v[98:101], v[180:183], v[196:199], v[98:101]
	v_mfma_f32_16x16x32_bf16 v[86:89], v[172:175], v[204:207], v[86:89]
	v_mfma_f32_16x16x32_bf16 v[82:85], v[180:183], v[204:207], v[82:85]
	v_mfma_f32_16x16x32_bf16 v[70:73], v[172:175], v[214:217], v[70:73]
	v_mfma_f32_16x16x32_bf16 v[66:69], v[180:183], v[214:217], v[66:69]
	v_mfma_f32_16x16x32_bf16 v[118:121], v[176:179], v[192:195], v[118:121]
	v_mfma_f32_16x16x32_bf16 v[114:117], v[184:187], v[192:195], v[114:117]
	v_mfma_f32_16x16x32_bf16 v[102:105], v[176:179], v[200:203], v[102:105]
	v_mfma_f32_16x16x32_bf16 v[98:101], v[184:187], v[200:203], v[98:101]
	v_mfma_f32_16x16x32_bf16 v[86:89], v[176:179], v[210:213], v[86:89]
	v_mfma_f32_16x16x32_bf16 v[82:85], v[184:187], v[210:213], v[82:85]
	v_mfma_f32_16x16x32_bf16 v[70:73], v[176:179], v[218:221], v[70:73]
	v_mfma_f32_16x16x32_bf16 v[66:69], v[184:187], v[218:221], v[66:69]
	s_setprio 0
	s_barrier
	s_add_i32 s81, s44, s35
	v_lshl_add_u64 v[222:223], s[28:29], 0, v[132:133]
	s_mov_b32 m0, s81
	ds_read_b128 v[188:191], v159 offset:16384
	ds_read_b128 v[192:195], v159 offset:17408
	ds_read_b128 v[196:199], v159 offset:18432
	ds_read_b128 v[200:203], v159 offset:19456
	ds_read_b128 v[204:207], v159 offset:20480
	ds_read_b128 v[210:213], v159 offset:21504
	ds_read_b128 v[214:217], v159 offset:22528
	ds_read_b128 v[218:221], v159 offset:23552
	global_load_lds_dwordx4 v[222:223], off
	s_add_i32 m0, s81, 0x2000
	s_add_u32 s82, s28, 0x40000
	v_lshl_add_u64 v[224:225], s[28:29], 0, v[136:137]
	s_addc_u32 s83, s29, 0
	s_add_i32 s81, s45, s35
	global_load_lds_dwordx4 v[224:225], off
	v_lshl_add_u64 v[226:227], s[82:83], 0, v[132:133]
	s_mov_b32 m0, s81
	v_lshl_add_u64 v[228:229], s[30:31], 0, v[134:135]
	global_load_lds_dwordx4 v[226:227], off
	v_lshl_add_u64 v[226:227], s[82:83], 0, v[136:137]
	s_add_i32 m0, s81, 0x2000
	s_nop 0
	global_load_lds_dwordx4 v[226:227], off
	v_lshl_add_u64 v[226:227], s[30:31], 0, v[130:131]
	s_mov_b32 m0, s9
	s_nop 0
	global_load_lds_dwordx4 v[226:227], off
	s_mov_b32 m0, s36
	s_nop 0
	global_load_lds_dwordx4 v[228:229], off
	s_waitcnt vmcnt(8)
	s_waitcnt lgkmcnt(0)
	s_barrier
	s_setprio 1
	s_waitcnt lgkmcnt(0)
	v_mfma_f32_16x16x32_bf16 v[62:65], v[152:155], v[188:191], v[62:65]
	v_mfma_f32_16x16x32_bf16 v[58:61], v[164:167], v[188:191], v[58:61]
	v_mfma_f32_16x16x32_bf16 v[46:49], v[152:155], v[196:199], v[46:49]
	v_mfma_f32_16x16x32_bf16 v[42:45], v[164:167], v[196:199], v[42:45]
	v_mfma_f32_16x16x32_bf16 v[30:33], v[152:155], v[204:207], v[30:33]
	v_mfma_f32_16x16x32_bf16 v[26:29], v[164:167], v[204:207], v[26:29]
	v_mfma_f32_16x16x32_bf16 v[14:17], v[152:155], v[214:217], v[14:17]
	v_mfma_f32_16x16x32_bf16 v[10:13], v[164:167], v[214:217], v[10:13]
	v_mfma_f32_16x16x32_bf16 v[62:65], v[160:163], v[192:195], v[62:65]
	v_mfma_f32_16x16x32_bf16 v[58:61], v[168:171], v[192:195], v[58:61]
	v_mfma_f32_16x16x32_bf16 v[46:49], v[160:163], v[200:203], v[46:49]
	v_mfma_f32_16x16x32_bf16 v[42:45], v[168:171], v[200:203], v[42:45]
	v_mfma_f32_16x16x32_bf16 v[30:33], v[160:163], v[210:213], v[30:33]
	v_mfma_f32_16x16x32_bf16 v[26:29], v[168:171], v[210:213], v[26:29]
	v_mfma_f32_16x16x32_bf16 v[14:17], v[160:163], v[218:221], v[14:17]
	v_mfma_f32_16x16x32_bf16 v[10:13], v[168:171], v[218:221], v[10:13]
	s_setprio 0
	s_setprio 1
	v_mfma_f32_16x16x32_bf16 v[54:57], v[172:175], v[188:191], v[54:57]
	v_mfma_f32_16x16x32_bf16 v[50:53], v[180:183], v[188:191], v[50:53]
	v_mfma_f32_16x16x32_bf16 v[38:41], v[172:175], v[196:199], v[38:41]
	v_mfma_f32_16x16x32_bf16 v[34:37], v[180:183], v[196:199], v[34:37]
	v_mfma_f32_16x16x32_bf16 v[22:25], v[172:175], v[204:207], v[22:25]
	v_mfma_f32_16x16x32_bf16 v[18:21], v[180:183], v[204:207], v[18:21]
	v_mfma_f32_16x16x32_bf16 v[6:9], v[172:175], v[214:217], v[6:9]
	v_mfma_f32_16x16x32_bf16 v[2:5], v[180:183], v[214:217], v[2:5]
	v_mfma_f32_16x16x32_bf16 v[54:57], v[176:179], v[192:195], v[54:57]
	v_mfma_f32_16x16x32_bf16 v[50:53], v[184:187], v[192:195], v[50:53]
	v_mfma_f32_16x16x32_bf16 v[38:41], v[176:179], v[200:203], v[38:41]
	v_mfma_f32_16x16x32_bf16 v[34:37], v[184:187], v[200:203], v[34:37]
	v_mfma_f32_16x16x32_bf16 v[22:25], v[176:179], v[210:213], v[22:25]
	v_mfma_f32_16x16x32_bf16 v[18:21], v[184:187], v[210:213], v[18:21]
	v_mfma_f32_16x16x32_bf16 v[6:9], v[176:179], v[218:221], v[6:9]
	v_mfma_f32_16x16x32_bf16 v[2:5], v[184:187], v[218:221], v[2:5]
	s_setprio 0
	s_barrier
	s_add_i32 s81, 0, 0x18000
	v_add_u32_e32 v138, s81, v156
	s_add_i32 s82, 0, 0x1c000
	ds_read_b128 v[152:155], v138
	ds_read_b128 v[160:163], v138 offset:1024
	ds_read_b128 v[164:167], v138 offset:2048
	ds_read_b128 v[168:171], v138 offset:3072
	v_add_u32_e32 v138, 0x1000, v138
	ds_read_b128 v[172:175], v138
	ds_read_b128 v[176:179], v138 offset:1024
	ds_read_b128 v[180:183], v138 offset:2048
	ds_read_b128 v[184:187], v138 offset:3072
	s_add_u32 s30, s30, 0x40000
	s_addc_u32 s31, s31, 0
	s_mov_b32 m0, s37
	v_lshl_add_u64 v[230:231], s[30:31], 0, v[130:131]
	ds_read_b128 v[188:191], v159 offset:32768
	ds_read_b128 v[192:195], v159 offset:33792
	ds_read_b128 v[196:199], v159 offset:34816
	ds_read_b128 v[200:203], v159 offset:35840
	ds_read_b128 v[204:207], v159 offset:36864
	ds_read_b128 v[210:213], v159 offset:37888
	ds_read_b128 v[214:217], v159 offset:38912
	ds_read_b128 v[218:221], v159 offset:39936
	global_load_lds_dwordx4 v[230:231], off
	v_lshl_add_u64 v[230:231], s[30:31], 0, v[134:135]
	s_mov_b32 m0, s38
	s_nop 0
	global_load_lds_dwordx4 v[230:231], off
	s_waitcnt vmcnt(8)
	s_waitcnt lgkmcnt(0)
	s_barrier
	s_setprio 1
	s_waitcnt lgkmcnt(0)
	v_mfma_f32_16x16x32_bf16 v[126:129], v[152:155], v[188:191], v[126:129]
	v_mfma_f32_16x16x32_bf16 v[122:125], v[164:167], v[188:191], v[122:125]
	v_mfma_f32_16x16x32_bf16 v[110:113], v[152:155], v[196:199], v[110:113]
	v_mfma_f32_16x16x32_bf16 v[106:109], v[164:167], v[196:199], v[106:109]
	v_mfma_f32_16x16x32_bf16 v[94:97], v[152:155], v[204:207], v[94:97]
	v_mfma_f32_16x16x32_bf16 v[90:93], v[164:167], v[204:207], v[90:93]
	v_mfma_f32_16x16x32_bf16 v[78:81], v[152:155], v[214:217], v[78:81]
	v_mfma_f32_16x16x32_bf16 v[74:77], v[164:167], v[214:217], v[74:77]
	v_mfma_f32_16x16x32_bf16 v[126:129], v[160:163], v[192:195], v[126:129]
	v_mfma_f32_16x16x32_bf16 v[122:125], v[168:171], v[192:195], v[122:125]
	v_mfma_f32_16x16x32_bf16 v[110:113], v[160:163], v[200:203], v[110:113]
	v_mfma_f32_16x16x32_bf16 v[106:109], v[168:171], v[200:203], v[106:109]
	v_mfma_f32_16x16x32_bf16 v[94:97], v[160:163], v[210:213], v[94:97]
	v_mfma_f32_16x16x32_bf16 v[90:93], v[168:171], v[210:213], v[90:93]
	v_mfma_f32_16x16x32_bf16 v[78:81], v[160:163], v[218:221], v[78:81]
	v_mfma_f32_16x16x32_bf16 v[74:77], v[168:171], v[218:221], v[74:77]
	s_setprio 0
	s_setprio 1
	v_mfma_f32_16x16x32_bf16 v[118:121], v[172:175], v[188:191], v[118:121]
	v_mfma_f32_16x16x32_bf16 v[114:117], v[180:183], v[188:191], v[114:117]
	v_mfma_f32_16x16x32_bf16 v[102:105], v[172:175], v[196:199], v[102:105]
	v_mfma_f32_16x16x32_bf16 v[98:101], v[180:183], v[196:199], v[98:101]
	v_mfma_f32_16x16x32_bf16 v[86:89], v[172:175], v[204:207], v[86:89]
	v_mfma_f32_16x16x32_bf16 v[82:85], v[180:183], v[204:207], v[82:85]
	v_mfma_f32_16x16x32_bf16 v[70:73], v[172:175], v[214:217], v[70:73]
	v_mfma_f32_16x16x32_bf16 v[66:69], v[180:183], v[214:217], v[66:69]
	v_mfma_f32_16x16x32_bf16 v[118:121], v[176:179], v[192:195], v[118:121]
	v_mfma_f32_16x16x32_bf16 v[114:117], v[184:187], v[192:195], v[114:117]
	v_mfma_f32_16x16x32_bf16 v[102:105], v[176:179], v[200:203], v[102:105]
	v_mfma_f32_16x16x32_bf16 v[98:101], v[184:187], v[200:203], v[98:101]
	v_mfma_f32_16x16x32_bf16 v[86:89], v[176:179], v[210:213], v[86:89]
	v_mfma_f32_16x16x32_bf16 v[82:85], v[184:187], v[210:213], v[82:85]
	v_mfma_f32_16x16x32_bf16 v[70:73], v[176:179], v[218:221], v[70:73]
	v_mfma_f32_16x16x32_bf16 v[66:69], v[184:187], v[218:221], v[66:69]
	s_setprio 0
	s_barrier
	s_add_i32 s30, s81, s35
	v_lshl_add_u64 v[222:223], v[222:223], 0, s[14:15]
	s_mov_b32 m0, s30
	ds_read_b128 v[188:191], v159 offset:49152
	ds_read_b128 v[192:195], v159 offset:50176
	ds_read_b128 v[196:199], v159 offset:51200
	ds_read_b128 v[200:203], v159 offset:52224
	ds_read_b128 v[204:207], v159 offset:53248
	ds_read_b128 v[210:213], v159 offset:54272
	ds_read_b128 v[214:217], v159 offset:55296
	ds_read_b128 v[218:221], v159 offset:56320
	global_load_lds_dwordx4 v[222:223], off
	s_add_i32 m0, s30, 0x2000
	s_add_u32 s28, s28, 0x40080
	v_lshl_add_u64 v[222:223], v[224:225], 0, s[14:15]
	s_addc_u32 s29, s29, 0
	s_add_i32 s30, s82, s35
	global_load_lds_dwordx4 v[222:223], off
	v_lshl_add_u64 v[222:223], s[28:29], 0, v[132:133]
	s_mov_b32 m0, s30
	s_nop 0
	global_load_lds_dwordx4 v[222:223], off
	v_lshl_add_u64 v[222:223], s[28:29], 0, v[136:137]
	s_add_i32 m0, s30, 0x2000
	s_nop 0
	global_load_lds_dwordx4 v[222:223], off
	v_lshl_add_u64 v[222:223], v[226:227], 0, s[14:15]
	s_mov_b32 m0, s40
	s_nop 0
	global_load_lds_dwordx4 v[222:223], off
	v_lshl_add_u64 v[222:223], v[228:229], 0, s[14:15]
	s_mov_b32 m0, s41
	s_nop 0
	global_load_lds_dwordx4 v[222:223], off
	s_waitcnt vmcnt(8)
	s_waitcnt lgkmcnt(0)
	s_barrier
	s_setprio 1
	s_waitcnt lgkmcnt(0)
	v_mfma_f32_16x16x32_bf16 v[62:65], v[152:155], v[188:191], v[62:65]
	v_mfma_f32_16x16x32_bf16 v[58:61], v[164:167], v[188:191], v[58:61]
	v_mfma_f32_16x16x32_bf16 v[46:49], v[152:155], v[196:199], v[46:49]
	v_mfma_f32_16x16x32_bf16 v[42:45], v[164:167], v[196:199], v[42:45]
	v_mfma_f32_16x16x32_bf16 v[30:33], v[152:155], v[204:207], v[30:33]
	v_mfma_f32_16x16x32_bf16 v[26:29], v[164:167], v[204:207], v[26:29]
	v_mfma_f32_16x16x32_bf16 v[14:17], v[152:155], v[214:217], v[14:17]
	v_mfma_f32_16x16x32_bf16 v[10:13], v[164:167], v[214:217], v[10:13]
	v_mfma_f32_16x16x32_bf16 v[62:65], v[160:163], v[192:195], v[62:65]
	v_mfma_f32_16x16x32_bf16 v[58:61], v[168:171], v[192:195], v[58:61]
	v_mfma_f32_16x16x32_bf16 v[46:49], v[160:163], v[200:203], v[46:49]
	v_mfma_f32_16x16x32_bf16 v[42:45], v[168:171], v[200:203], v[42:45]
	v_mfma_f32_16x16x32_bf16 v[30:33], v[160:163], v[210:213], v[30:33]
	v_mfma_f32_16x16x32_bf16 v[26:29], v[168:171], v[210:213], v[26:29]
	v_mfma_f32_16x16x32_bf16 v[14:17], v[160:163], v[218:221], v[14:17]
	v_mfma_f32_16x16x32_bf16 v[10:13], v[168:171], v[218:221], v[10:13]
	s_setprio 0
	s_setprio 1
	v_mfma_f32_16x16x32_bf16 v[54:57], v[172:175], v[188:191], v[54:57]
	v_mfma_f32_16x16x32_bf16 v[50:53], v[180:183], v[188:191], v[50:53]
	v_mfma_f32_16x16x32_bf16 v[38:41], v[172:175], v[196:199], v[38:41]
	v_mfma_f32_16x16x32_bf16 v[34:37], v[180:183], v[196:199], v[34:37]
	v_mfma_f32_16x16x32_bf16 v[22:25], v[172:175], v[204:207], v[22:25]
	v_mfma_f32_16x16x32_bf16 v[18:21], v[180:183], v[204:207], v[18:21]
	v_mfma_f32_16x16x32_bf16 v[6:9], v[172:175], v[214:217], v[6:9]
	v_mfma_f32_16x16x32_bf16 v[2:5], v[180:183], v[214:217], v[2:5]
	v_mfma_f32_16x16x32_bf16 v[54:57], v[176:179], v[192:195], v[54:57]
	v_mfma_f32_16x16x32_bf16 v[50:53], v[184:187], v[192:195], v[50:53]
	v_mfma_f32_16x16x32_bf16 v[38:41], v[176:179], v[200:203], v[38:41]
	v_mfma_f32_16x16x32_bf16 v[34:37], v[184:187], v[200:203], v[34:37]
	v_mfma_f32_16x16x32_bf16 v[22:25], v[176:179], v[210:213], v[22:25]
	v_mfma_f32_16x16x32_bf16 v[18:21], v[184:187], v[210:213], v[18:21]
	v_mfma_f32_16x16x32_bf16 v[6:9], v[176:179], v[218:221], v[6:9]
	v_mfma_f32_16x16x32_bf16 v[2:5], v[184:187], v[218:221], v[2:5]
	s_setprio 0
	s_barrier
	s_add_i32 s80, s80, 2
	s_add_u32 s26, s26, 0x100
	s_addc_u32 s27, s27, 0
	s_add_u32 s58, s58, 0x100
	s_addc_u32 s59, s59, 0
	s_cmp_gt_u32 s80, 13
	s_cbranch_scc0 .LBB0_374
	s_and_b64 vcc, exec, s[16:17]
	s_cbranch_vccz .LBB0_377
	s_barrier
.LBB0_377:
	v_lshl_add_u32 v152, s6, 8, v141
	s_cmp_lg_u32 s8, 14
	s_cbranch_scc0 .Lp1e_lra
	v_and_b32_e32 v153, 8, v141
	v_sub_u32_e32 v160, v152, v153
	v_mul_u32_u24_e32 v160, 0x1c00, v160
	v_and_b32_e32 v161, 0x60, v140
	v_add_u32_e32 v161, v161, v140
	v_lshl_add_u32 v161, v153, 2, v161
	s_lshl_b32 s26, s8, 9
	v_lshl_add_u32 v161, v161, 1, s26
	v_add_u32_e32 v160, v160, v161
	s_mov_b32 s26, s12
	s_mov_b32 s27, s13
	v_cvt_pk_bf16_f32 v168, v118, v119
	v_cvt_pk_bf16_f32 v169, v120, v121
	v_cvt_pk_bf16_f32 v170, v114, v115
	v_cvt_pk_bf16_f32 v171, v116, v117
	v_cvt_pk_bf16_f32 v164, v126, v127
	v_cvt_pk_bf16_f32 v165, v128, v129
	v_cvt_pk_bf16_f32 v166, v122, v123
	v_cvt_pk_bf16_f32 v167, v124, v125
	v_mov_b32_e32 v172, v164
	v_mov_b32_e32 v173, v165
	v_mov_b32_e32 v174, v166
	v_mov_b32_e32 v175, v167
	v_mov_b32_dpp v172, v168 row_shr:8 row_mask:0xf bank_mask:0xc
	v_mov_b32_dpp v173, v169 row_shr:8 row_mask:0xf bank_mask:0xc
	v_mov_b32_dpp v174, v170 row_shr:8 row_mask:0xf bank_mask:0xc
	v_mov_b32_dpp v175, v171 row_shr:8 row_mask:0xf bank_mask:0xc
	v_mov_b32_dpp v168, v164 row_shl:8 row_mask:0xf bank_mask:0x3
	v_mov_b32_dpp v169, v165 row_shl:8 row_mask:0xf bank_mask:0x3
	v_mov_b32_dpp v170, v166 row_shl:8 row_mask:0xf bank_mask:0x3
	v_mov_b32_dpp v171, v167 row_shl:8 row_mask:0xf bank_mask:0x3
	global_store_dwordx4 v160, v[172:175], s[26:27]
	s_add_u32 s26, s26, 0xe000
	s_addc_u32 s27, s27, 0
	global_store_dwordx4 v160, v[168:171], s[26:27]
	s_add_u32 s26, s26, 0xe000
	s_addc_u32 s27, s27, 0
	v_cvt_pk_bf16_f32 v180, v102, v103
	v_cvt_pk_bf16_f32 v181, v104, v105
	v_cvt_pk_bf16_f32 v182, v98, v99
	v_cvt_pk_bf16_f32 v183, v100, v101
	v_cvt_pk_bf16_f32 v176, v110, v111
	v_cvt_pk_bf16_f32 v177, v112, v113
	v_cvt_pk_bf16_f32 v178, v106, v107
	v_cvt_pk_bf16_f32 v179, v108, v109
	v_mov_b32_e32 v184, v176
	v_mov_b32_e32 v185, v177
	v_mov_b32_e32 v186, v178
	v_mov_b32_e32 v187, v179
	v_mov_b32_dpp v184, v180 row_shr:8 row_mask:0xf bank_mask:0xc
	v_mov_b32_dpp v185, v181 row_shr:8 row_mask:0xf bank_mask:0xc
	v_mov_b32_dpp v186, v182 row_shr:8 row_mask:0xf bank_mask:0xc
	v_mov_b32_dpp v187, v183 row_shr:8 row_mask:0xf bank_mask:0xc
	v_mov_b32_dpp v180, v176 row_shl:8 row_mask:0xf bank_mask:0x3
	v_mov_b32_dpp v181, v177 row_shl:8 row_mask:0xf bank_mask:0x3
	v_mov_b32_dpp v182, v178 row_shl:8 row_mask:0xf bank_mask:0x3
	v_mov_b32_dpp v183, v179 row_shl:8 row_mask:0xf bank_mask:0x3
	global_store_dwordx4 v160, v[184:187], s[26:27]
	s_add_u32 s26, s26, 0xe000
	s_addc_u32 s27, s27, 0
	global_store_dwordx4 v160, v[180:183], s[26:27]
	s_add_u32 s26, s26, 0xe000
	s_addc_u32 s27, s27, 0
	v_cvt_pk_bf16_f32 v168, v86, v87
	v_cvt_pk_bf16_f32 v169, v88, v89
	v_cvt_pk_bf16_f32 v170, v82, v83
	v_cvt_pk_bf16_f32 v171, v84, v85
	v_cvt_pk_bf16_f32 v164, v94, v95
	v_cvt_pk_bf16_f32 v165, v96, v97
	v_cvt_pk_bf16_f32 v166, v90, v91
	v_cvt_pk_bf16_f32 v167, v92, v93
	v_mov_b32_e32 v172, v164
	v_mov_b32_e32 v173, v165
	v_mov_b32_e32 v174, v166
	v_mov_b32_e32 v175, v167
	v_mov_b32_dpp v172, v168 row_shr:8 row_mask:0xf bank_mask:0xc
	v_mov_b32_dpp v173, v169 row_shr:8 row_mask:0xf bank_mask:0xc
	v_mov_b32_dpp v174, v170 row_shr:8 row_mask:0xf bank_mask:0xc
	v_mov_b32_dpp v175, v171 row_shr:8 row_mask:0xf bank_mask:0xc
	v_mov_b32_dpp v168, v164 row_shl:8 row_mask:0xf bank_mask:0x3
	v_mov_b32_dpp v169, v165 row_shl:8 row_mask:0xf bank_mask:0x3
	v_mov_b32_dpp v170, v166 row_shl:8 row_mask:0xf bank_mask:0x3
	v_mov_b32_dpp v171, v167 row_shl:8 row_mask:0xf bank_mask:0x3
	global_store_dwordx4 v160, v[172:175], s[26:27]
	s_add_u32 s26, s26, 0xe000
	s_addc_u32 s27, s27, 0
	global_store_dwordx4 v160, v[168:171], s[26:27]
	s_add_u32 s26, s26, 0xe000
	s_addc_u32 s27, s27, 0
	v_cvt_pk_bf16_f32 v180, v70, v71
	v_cvt_pk_bf16_f32 v181, v72, v73
	v_cvt_pk_bf16_f32 v182, v66, v67
	v_cvt_pk_bf16_f32 v183, v68, v69
	v_cvt_pk_bf16_f32 v176, v78, v79
	v_cvt_pk_bf16_f32 v177, v80, v81
	v_cvt_pk_bf16_f32 v178, v74, v75
	v_cvt_pk_bf16_f32 v179, v76, v77
	v_mov_b32_e32 v184, v176
	v_mov_b32_e32 v185, v177
	v_mov_b32_e32 v186, v178
	v_mov_b32_e32 v187, v179
	v_mov_b32_dpp v184, v180 row_shr:8 row_mask:0xf bank_mask:0xc
	v_mov_b32_dpp v185, v181 row_shr:8 row_mask:0xf bank_mask:0xc
	v_mov_b32_dpp v186, v182 row_shr:8 row_mask:0xf bank_mask:0xc
	v_mov_b32_dpp v187, v183 row_shr:8 row_mask:0xf bank_mask:0xc
	v_mov_b32_dpp v180, v176 row_shl:8 row_mask:0xf bank_mask:0x3
	v_mov_b32_dpp v181, v177 row_shl:8 row_mask:0xf bank_mask:0x3
	v_mov_b32_dpp v182, v178 row_shl:8 row_mask:0xf bank_mask:0x3
	v_mov_b32_dpp v183, v179 row_shl:8 row_mask:0xf bank_mask:0x3
	global_store_dwordx4 v160, v[184:187], s[26:27]
	s_add_u32 s26, s26, 0xe000
	s_addc_u32 s27, s27, 0
	global_store_dwordx4 v160, v[180:183], s[26:27]
	s_add_u32 s26, s26, 0x7e000
	s_addc_u32 s27, s27, 0
	v_cvt_pk_bf16_f32 v168, v54, v55
	v_cvt_pk_bf16_f32 v169, v56, v57
	v_cvt_pk_bf16_f32 v170, v50, v51
	v_cvt_pk_bf16_f32 v171, v52, v53
	v_cvt_pk_bf16_f32 v164, v62, v63
	v_cvt_pk_bf16_f32 v165, v64, v65
	v_cvt_pk_bf16_f32 v166, v58, v59
	v_cvt_pk_bf16_f32 v167, v60, v61
	v_mov_b32_e32 v172, v164
	v_mov_b32_e32 v173, v165
	v_mov_b32_e32 v174, v166
	v_mov_b32_e32 v175, v167
	v_mov_b32_dpp v172, v168 row_shr:8 row_mask:0xf bank_mask:0xc
	v_mov_b32_dpp v173, v169 row_shr:8 row_mask:0xf bank_mask:0xc
	v_mov_b32_dpp v174, v170 row_shr:8 row_mask:0xf bank_mask:0xc
	v_mov_b32_dpp v175, v171 row_shr:8 row_mask:0xf bank_mask:0xc
	v_mov_b32_dpp v168, v164 row_shl:8 row_mask:0xf bank_mask:0x3
	v_mov_b32_dpp v169, v165 row_shl:8 row_mask:0xf bank_mask:0x3
	v_mov_b32_dpp v170, v166 row_shl:8 row_mask:0xf bank_mask:0x3
	v_mov_b32_dpp v171, v167 row_shl:8 row_mask:0xf bank_mask:0x3
	global_store_dwordx4 v160, v[172:175], s[26:27]
	s_add_u32 s26, s26, 0xe000
	s_addc_u32 s27, s27, 0
	global_store_dwordx4 v160, v[168:171], s[26:27]
	s_add_u32 s26, s26, 0xe000
	s_addc_u32 s27, s27, 0
	v_cvt_pk_bf16_f32 v180, v38, v39
	v_cvt_pk_bf16_f32 v181, v40, v41
	v_cvt_pk_bf16_f32 v182, v34, v35
	v_cvt_pk_bf16_f32 v183, v36, v37
	v_cvt_pk_bf16_f32 v176, v46, v47
	v_cvt_pk_bf16_f32 v177, v48, v49
	v_cvt_pk_bf16_f32 v178, v42, v43
	v_cvt_pk_bf16_f32 v179, v44, v45
	v_mov_b32_e32 v184, v176
	v_mov_b32_e32 v185, v177
	v_mov_b32_e32 v186, v178
	v_mov_b32_e32 v187, v179
	v_mov_b32_dpp v184, v180 row_shr:8 row_mask:0xf bank_mask:0xc
	v_mov_b32_dpp v185, v181 row_shr:8 row_mask:0xf bank_mask:0xc
	v_mov_b32_dpp v186, v182 row_shr:8 row_mask:0xf bank_mask:0xc
	v_mov_b32_dpp v187, v183 row_shr:8 row_mask:0xf bank_mask:0xc
	v_mov_b32_dpp v180, v176 row_shl:8 row_mask:0xf bank_mask:0x3
	v_mov_b32_dpp v181, v177 row_shl:8 row_mask:0xf bank_mask:0x3
	v_mov_b32_dpp v182, v178 row_shl:8 row_mask:0xf bank_mask:0x3
	v_mov_b32_dpp v183, v179 row_shl:8 row_mask:0xf bank_mask:0x3
	global_store_dwordx4 v160, v[184:187], s[26:27]
	s_add_u32 s26, s26, 0xe000
	s_addc_u32 s27, s27, 0
	global_store_dwordx4 v160, v[180:183], s[26:27]
	s_add_u32 s26, s26, 0xe000
	s_addc_u32 s27, s27, 0
	v_cvt_pk_bf16_f32 v168, v22, v23
	v_cvt_pk_bf16_f32 v169, v24, v25
	v_cvt_pk_bf16_f32 v170, v18, v19
	v_cvt_pk_bf16_f32 v171, v20, v21
	v_cvt_pk_bf16_f32 v164, v30, v31
	v_cvt_pk_bf16_f32 v165, v32, v33
	v_cvt_pk_bf16_f32 v166, v26, v27
	v_cvt_pk_bf16_f32 v167, v28, v29
	v_mov_b32_e32 v172, v164
	v_mov_b32_e32 v173, v165
	v_mov_b32_e32 v174, v166
	v_mov_b32_e32 v175, v167
	v_mov_b32_dpp v172, v168 row_shr:8 row_mask:0xf bank_mask:0xc
	v_mov_b32_dpp v173, v169 row_shr:8 row_mask:0xf bank_mask:0xc
	v_mov_b32_dpp v174, v170 row_shr:8 row_mask:0xf bank_mask:0xc
	v_mov_b32_dpp v175, v171 row_shr:8 row_mask:0xf bank_mask:0xc
	v_mov_b32_dpp v168, v164 row_shl:8 row_mask:0xf bank_mask:0x3
	v_mov_b32_dpp v169, v165 row_shl:8 row_mask:0xf bank_mask:0x3
	v_mov_b32_dpp v170, v166 row_shl:8 row_mask:0xf bank_mask:0x3
	v_mov_b32_dpp v171, v167 row_shl:8 row_mask:0xf bank_mask:0x3
	global_store_dwordx4 v160, v[172:175], s[26:27]
	s_add_u32 s26, s26, 0xe000
	s_addc_u32 s27, s27, 0
	global_store_dwordx4 v160, v[168:171], s[26:27]
	s_add_u32 s26, s26, 0xe000
	s_addc_u32 s27, s27, 0
	v_cvt_pk_bf16_f32 v180, v6, v7
	v_cvt_pk_bf16_f32 v181, v8, v9
	v_cvt_pk_bf16_f32 v182, v2, v3
	v_cvt_pk_bf16_f32 v183, v4, v5
	v_cvt_pk_bf16_f32 v176, v14, v15
	v_cvt_pk_bf16_f32 v177, v16, v17
	v_cvt_pk_bf16_f32 v178, v10, v11
	v_cvt_pk_bf16_f32 v179, v12, v13
	v_mov_b32_e32 v184, v176
	v_mov_b32_e32 v185, v177
	v_mov_b32_e32 v186, v178
	v_mov_b32_e32 v187, v179
	v_mov_b32_dpp v184, v180 row_shr:8 row_mask:0xf bank_mask:0xc
	v_mov_b32_dpp v185, v181 row_shr:8 row_mask:0xf bank_mask:0xc
	v_mov_b32_dpp v186, v182 row_shr:8 row_mask:0xf bank_mask:0xc
	v_mov_b32_dpp v187, v183 row_shr:8 row_mask:0xf bank_mask:0xc
	v_mov_b32_dpp v180, v176 row_shl:8 row_mask:0xf bank_mask:0x3
	v_mov_b32_dpp v181, v177 row_shl:8 row_mask:0xf bank_mask:0x3
	v_mov_b32_dpp v182, v178 row_shl:8 row_mask:0xf bank_mask:0x3
	v_mov_b32_dpp v183, v179 row_shl:8 row_mask:0xf bank_mask:0x3
	global_store_dwordx4 v160, v[184:187], s[26:27]
	s_add_u32 s26, s26, 0xe000
	s_addc_u32 s27, s27, 0
	global_store_dwordx4 v160, v[180:183], s[26:27]
	s_branch .LBB0_441
.Lp1e_lra:
	s_and_saveexec_b64 s[26:27], s[2:3]
	s_cbranch_execz .Lp1e_lra_done
	v_ashrrev_i32_e32 v153, 31, v152
	v_lshlrev_b64 v[160:161], 6, v[152:153]
	v_lshl_add_u64 v[160:161], v[142:143], 0, v[160:161]
	global_store_dwordx4 v[160:161], v[126:129], off
	global_store_dwordx4 v[160:161], v[122:125], off offset:16
	global_store_dwordx4 v[160:161], v[110:113], off offset:1024
	global_store_dwordx4 v[160:161], v[106:109], off offset:1040
	global_store_dwordx4 v[160:161], v[94:97], off offset:2048
	global_store_dwordx4 v[160:161], v[90:93], off offset:2064
	global_store_dwordx4 v[160:161], v[78:81], off offset:3072
	global_store_dwordx4 v[160:161], v[74:77], off offset:3088
	v_add_co_u32_e32 v160, vcc, 0x2000, v160
	s_nop 1
	v_addc_co_u32_e32 v161, vcc, 0, v161, vcc
	global_store_dwordx4 v[160:161], v[62:65], off
	global_store_dwordx4 v[160:161], v[58:61], off offset:16
	global_store_dwordx4 v[160:161], v[46:49], off offset:1024
	global_store_dwordx4 v[160:161], v[42:45], off offset:1040
	global_store_dwordx4 v[160:161], v[30:33], off offset:2048
	global_store_dwordx4 v[160:161], v[26:29], off offset:2064
	global_store_dwordx4 v[160:161], v[14:17], off offset:3072
	global_store_dwordx4 v[160:161], v[10:13], off offset:3088
.Lp1e_lra_done:
	s_or_b64 exec, exec, s[26:27]
.LBB0_441:
	s_andn2_b64 vcc, exec, s[4:5]
	s_mov_b64 s[4:5], -1
	s_cbranch_vccnz .LBB0_366
